# plus: attention-output and spatial-gating epilogue stores widened to dwordx4 via permlane32 swaps
# baseline (speedup 1.0000x reference)
.LBB0_675:
	s_and_b32 s0, s4, 0xffffff80
	s_and_b32 s2, s6, 7
	s_ashr_i32 s1, s0, 31
	v_lshl_add_u32 v6, s2, 8, v117
	v_lshl_add_u64 v[2:3], s[0:1], 1, v[70:71]
	v_mad_i64_i32 v[4:5], s[8:9], v6, s7, v[2:3]
	global_load_dwordx4 v[38:41], v[4:5], off
	v_add_u32_e32 v4, 32, v6
	v_mad_i64_i32 v[4:5], s[8:9], v4, s7, v[2:3]
	global_load_dwordx4 v[42:45], v[4:5], off
	v_add_u32_e32 v4, 64, v6
	v_mad_i64_i32 v[4:5], s[8:9], v4, s7, v[2:3]
	global_load_dwordx4 v[46:49], v[4:5], off
	v_add_u32_e32 v4, 0x60, v6
	v_mad_i64_i32 v[4:5], s[8:9], v4, s7, v[2:3]
	global_load_dwordx4 v[50:53], v[4:5], off
	v_add_u32_e32 v4, 0x80, v6
	v_mad_i64_i32 v[4:5], s[8:9], v4, s7, v[2:3]
	global_load_dwordx4 v[54:57], v[4:5], off
	v_add_u32_e32 v4, 0xa0, v6
	v_mad_i64_i32 v[4:5], s[8:9], v4, s7, v[2:3]
	global_load_dwordx4 v[58:61], v[4:5], off
	v_add_u32_e32 v4, 0xc0, v6
	v_mad_i64_i32 v[4:5], s[8:9], v4, s7, v[2:3]
	global_load_dwordx4 v[62:65], v[4:5], off
	v_add_u32_e32 v4, 0xe0, v6
	v_mad_i64_i32 v[2:3], s[8:9], v4, s7, v[2:3]
	v_lshl_add_u64 v[34:35], s[0:1], 2, v[76:77]
	global_load_dwordx4 v[66:69], v[2:3], off
	s_lshl_b32 s30, s2, 7
	global_load_dwordx4 v[34:37], v[34:35], off
	v_lshl_add_u64 v[2:3], s[30:31], 0, v[72:73]
	v_lshlrev_b64 v[2:3], 9, v[2:3]
	v_lshl_add_u64 v[2:3], v[74:75], 0, v[2:3]
	s_movk_i32 s3, 0x2000
	v_add_co_u32_e32 v4, vcc, s3, v2
	s_movk_i32 s3, 0x4000
	s_nop 0
	v_addc_co_u32_e32 v5, vcc, 0, v3, vcc
	global_load_dwordx4 v[6:9], v[2:3], off
	global_load_dwordx4 v[30:33], v[4:5], off
	v_add_co_u32_e32 v4, vcc, s3, v2
	s_mov_b32 s3, 0x8000
	s_nop 0
	v_addc_co_u32_e32 v5, vcc, 0, v3, vcc
	global_load_dwordx4 v[26:29], v[4:5], off
	v_add_co_u32_e32 v4, vcc, s7, v2
	v_or_b32_e32 v82, s0, v116
	s_nop 0
	v_addc_co_u32_e32 v5, vcc, 0, v3, vcc
	global_load_dwordx4 v[22:25], v[4:5], off
	v_add_co_u32_e32 v4, vcc, s3, v2
	s_mov_b32 s3, 0xa000
	s_nop 0
	v_addc_co_u32_e32 v5, vcc, 0, v3, vcc
	global_load_dwordx4 v[18:21], v[4:5], off
	v_add_co_u32_e32 v4, vcc, s3, v2
	s_mov_b32 s3, 0xc000
	s_nop 0
	v_addc_co_u32_e32 v5, vcc, 0, v3, vcc
	global_load_dwordx4 v[14:17], v[4:5], off
	v_add_co_u32_e32 v4, vcc, s3, v2
	s_mov_b32 s3, 0xe000
	s_nop 0
	v_addc_co_u32_e32 v5, vcc, 0, v3, vcc
	v_add_co_u32_e32 v2, vcc, s3, v2
	global_load_dwordx4 v[10:13], v[4:5], off
	s_nop 0
	v_addc_co_u32_e32 v3, vcc, 0, v3, vcc
	global_load_dwordx4 v[2:5], v[2:3], off
	v_ashrrev_i32_e32 v83, 31, v82
	v_lshlrev_b64 v[82:83], 12, v[82:83]
	v_lshl_add_u64 v[82:83], s[18:19], 0, v[82:83]
	s_lshl_b32 s0, s2, 9
	s_mov_b32 s1, s31
	v_lshl_add_u64 v[114:115], v[82:83], 0, s[0:1]
	v_lshl_add_u64 v[82:83], s[34:35], 1, v[114:115]
	v_lshl_add_u64 v[82:83], v[82:83], 0, v[0:1]
	global_load_dwordx2 v[112:113], v[82:83], off
	global_load_dwordx2 v[110:111], v[82:83], off offset:16
	global_load_dwordx2 v[108:109], v[82:83], off offset:32
	global_load_dwordx2 v[106:107], v[82:83], off offset:48
	global_load_dwordx2 v[104:105], v[82:83], off offset:64
	global_load_dwordx2 v[102:103], v[82:83], off offset:80
	global_load_dwordx2 v[100:101], v[82:83], off offset:96
	global_load_dwordx2 v[98:99], v[82:83], off offset:112
	global_load_dwordx2 v[96:97], v[82:83], off offset:128
	global_load_dwordx2 v[94:95], v[82:83], off offset:144
	global_load_dwordx2 v[92:93], v[82:83], off offset:160
	global_load_dwordx2 v[90:91], v[82:83], off offset:176
	global_load_dwordx2 v[88:89], v[82:83], off offset:192
	global_load_dwordx2 v[86:87], v[82:83], off offset:208
	global_load_dwordx2 v[84:85], v[82:83], off offset:224
	s_nop 0
	global_load_dwordx2 v[82:83], v[82:83], off offset:240
	s_waitcnt vmcnt(0)
	s_barrier
	ds_write_b128 v118, v[38:41]
	ds_write_b128 v118, v[42:45] offset:8704
	ds_write_b128 v118, v[46:49] offset:17408
	ds_write_b128 v118, v[50:53] offset:26112
	ds_write_b128 v118, v[54:57] offset:34816
	ds_write_b128 v118, v[58:61] offset:43520
	ds_write_b128 v118, v[62:65] offset:52224
	ds_write_b128 v118, v[66:69] offset:60928
	v_mov_b64_e32 v[38:39], s[10:11]
	v_lshl_add_u64 v[52:53], v[80:81], 1, v[114:115]
	v_and_b32_e32 v134, 32, v214
	v_lshrrev_b32_e32 v134, 2, v134
	v_mov_b32_e32 v135, 0
	v_lshl_add_u64 v[52:53], v[52:53], 0, v[134:135]
	s_add_i32 s6, s6, s85
	s_add_i32 s4, s4, s5
	v_pk_fma_f32 v[34:35], v[34:35], s[14:15], v[38:39] op_sel_hi:[1,0,0]
	s_nop 0
	v_mul_f32_e32 v40, 0x4b800000, v34
	v_cmp_gt_f32_e64 s[0:1], s68, v34
	v_cmp_gt_f32_e32 vcc, s68, v35
	v_pk_fma_f32 v[36:37], v[36:37], s[14:15], v[38:39] op_sel_hi:[1,0,0]
	v_cndmask_b32_e64 v34, v34, v40, s[0:1]
	v_mul_f32_e32 v40, 0x4b800000, v35
	v_cndmask_b32_e32 v35, v35, v40, vcc
	v_rsq_f32_e32 v34, v34
	v_rsq_f32_e32 v35, v35
	v_mul_f32_e32 v38, 0x4b800000, v36
	v_pk_mul_f32 v[40:41], v[34:35], s[12:13] op_sel_hi:[1,0]
	s_nop 0
	v_cndmask_b32_e64 v34, v34, v40, s[0:1]
	v_cmp_gt_f32_e64 s[0:1], s68, v36
	v_cndmask_b32_e32 v35, v35, v41, vcc
	v_cmp_gt_f32_e32 vcc, s68, v37
	v_cndmask_b32_e64 v36, v36, v38, s[0:1]
	v_mul_f32_e32 v38, 0x4b800000, v37
	v_cndmask_b32_e32 v37, v37, v38, vcc
	v_rsq_f32_e32 v36, v36
	v_rsq_f32_e32 v37, v37
	v_pk_mul_f32 v[6:7], v[6:7], v[34:35]
	v_pk_mul_f32 v[38:39], v[36:37], s[12:13] op_sel_hi:[1,0]
	s_nop 0
	v_cndmask_b32_e32 v37, v37, v39, vcc
	v_cndmask_b32_e64 v36, v36, v38, s[0:1]
	v_pk_mul_f32 v[8:9], v[8:9], v[36:37]
	v_cvt_pk_bf16_f32 v6, v6, v7
	v_cvt_pk_bf16_f32 v7, v8, v9
	ds_write_b64 v119, v[6:7]
	v_pk_mul_f32 v[6:7], v[32:33], v[36:37]
	v_pk_mul_f32 v[8:9], v[30:31], v[34:35]
	v_and_b32_e32 v69, 0xffff0000, v112
	v_cvt_pk_bf16_f32 v8, v8, v9
	v_cvt_pk_bf16_f32 v9, v6, v7
	ds_write_b64 v119, v[8:9] offset:4352
	v_pk_mul_f32 v[6:7], v[28:29], v[36:37]
	v_pk_mul_f32 v[8:9], v[26:27], v[34:35]
	v_pk_mul_f32 v[4:5], v[4:5], v[36:37]
	v_cvt_pk_bf16_f32 v8, v8, v9
	v_cvt_pk_bf16_f32 v9, v6, v7
	ds_write_b64 v119, v[8:9] offset:8704
	v_pk_mul_f32 v[6:7], v[24:25], v[36:37]
	v_pk_mul_f32 v[8:9], v[22:23], v[34:35]
	v_pk_mul_f32 v[2:3], v[2:3], v[34:35]
	v_cvt_pk_bf16_f32 v8, v8, v9
	v_cvt_pk_bf16_f32 v9, v6, v7
	ds_write_b64 v119, v[8:9] offset:13056
	v_pk_mul_f32 v[6:7], v[20:21], v[36:37]
	v_pk_mul_f32 v[8:9], v[18:19], v[34:35]
	v_cvt_pk_bf16_f32 v2, v2, v3
	v_cvt_pk_bf16_f32 v8, v8, v9
	v_cvt_pk_bf16_f32 v9, v6, v7
	ds_write_b64 v119, v[8:9] offset:17408
	v_pk_mul_f32 v[6:7], v[16:17], v[36:37]
	v_pk_mul_f32 v[8:9], v[14:15], v[34:35]
	v_cvt_pk_bf16_f32 v3, v4, v5
	v_cvt_pk_bf16_f32 v8, v8, v9
	v_cvt_pk_bf16_f32 v9, v6, v7
	ds_write_b64 v119, v[8:9] offset:21760
	v_pk_mul_f32 v[6:7], v[12:13], v[36:37]
	v_pk_mul_f32 v[8:9], v[10:11], v[34:35]
	ds_write_b64 v119, v[2:3] offset:30464
	v_or_b32_e32 v2, s30, v116
	v_cvt_pk_bf16_f32 v8, v8, v9
	v_cvt_pk_bf16_f32 v9, v6, v7
	v_lshlrev_b32_e32 v2, 2, v2
	ds_write_b64 v119, v[8:9] offset:26112
	s_waitcnt lgkmcnt(0)
	s_barrier
	ds_read_b128 v[46:49], v120
	ds_read_b128 v[42:45], v120 offset:32
	ds_read_b128 v[38:41], v120 offset:64
	ds_read_b128 v[34:37], v120 offset:96
	ds_read_b128 v[30:33], v120 offset:128
	ds_read_b128 v[26:29], v120 offset:160
	ds_read_b128 v[22:25], v120 offset:192
	ds_read_b128 v[18:21], v120 offset:224
	global_load_dword v50, v2, s[54:55]
	s_lshl_b32 s30, s2, 10
	v_lshl_add_u64 v[54:55], v[78:79], 0, s[30:31]
	global_load_dwordx4 v[56:59], v[54:55], off
	global_load_dwordx4 v[60:63], v[54:55], off offset:32
	global_load_dwordx4 v[64:67], v[54:55], off offset:64
	global_load_dwordx4 v[122:125], v[54:55], off offset:96
	ds_read_b128 v[2:5], v121
	ds_read_b128 v[126:129], v121 offset:32
	s_waitcnt lgkmcnt(1)
	v_mfma_f32_32x32x16_bf16 v[2:17], v[2:5], v[46:49], 0
	v_lshlrev_b32_e32 v68, 16, v112
	s_cmpk_gt_i32 s6, 0x2ff
	s_waitcnt lgkmcnt(0)
	v_mfma_f32_32x32x16_bf16 v[2:17], v[126:129], v[42:45], v[2:17]
	ds_read_b128 v[126:129], v121 offset:64
	s_waitcnt lgkmcnt(0)
	v_mfma_f32_32x32x16_bf16 v[2:17], v[126:129], v[38:41], v[2:17]
	ds_read_b128 v[126:129], v121 offset:96
	s_waitcnt lgkmcnt(0)
	v_mfma_f32_32x32x16_bf16 v[2:17], v[126:129], v[34:37], v[2:17]
	ds_read_b128 v[126:129], v121 offset:128
	s_waitcnt lgkmcnt(0)
	v_mfma_f32_32x32x16_bf16 v[2:17], v[126:129], v[30:33], v[2:17]
	ds_read_b128 v[126:129], v121 offset:160
	s_waitcnt lgkmcnt(0)
	v_mfma_f32_32x32x16_bf16 v[2:17], v[126:129], v[26:29], v[2:17]
	ds_read_b128 v[126:129], v121 offset:192
	s_waitcnt lgkmcnt(0)
	v_mfma_f32_32x32x16_bf16 v[2:17], v[126:129], v[22:25], v[2:17]
	ds_read_b128 v[126:129], v121 offset:224
	s_waitcnt lgkmcnt(0)
	v_mfma_f32_32x32x16_bf16 v[2:17], v[126:129], v[18:21], v[2:17]
	s_waitcnt vmcnt(3)
	s_nop 10
	v_pk_fma_f32 v[2:3], v[56:57], v[2:3], v[50:51] op_sel_hi:[1,1,0]
	v_and_b32_e32 v57, 0xffff0000, v113
	v_lshlrev_b32_e32 v56, 16, v113
	v_pk_fma_f32 v[4:5], v[58:59], v[4:5], v[50:51] op_sel_hi:[1,1,0]
	v_pk_mul_f32 v[2:3], v[2:3], v[68:69]
	v_pk_mul_f32 v[4:5], v[4:5], v[56:57]
	v_cvt_pk_bf16_f32 v130, v2, v3
	v_cvt_pk_bf16_f32 v131, v4, v5
	v_and_b32_e32 v3, 0xffff0000, v110
	v_lshlrev_b32_e32 v2, 16, v110
	s_waitcnt vmcnt(2)
	v_pk_fma_f32 v[4:5], v[60:61], v[6:7], v[50:51] op_sel_hi:[1,1,0]
	v_pk_fma_f32 v[6:7], v[62:63], v[8:9], v[50:51] op_sel_hi:[1,1,0]
	v_pk_mul_f32 v[2:3], v[4:5], v[2:3]
	v_and_b32_e32 v5, 0xffff0000, v111
	v_lshlrev_b32_e32 v4, 16, v111
	v_pk_mul_f32 v[4:5], v[6:7], v[4:5]
	v_cvt_pk_bf16_f32 v132, v2, v3
	v_cvt_pk_bf16_f32 v133, v4, v5
	s_nop 1
	v_permlane32_swap_b32_e32 v130, v132
	v_permlane32_swap_b32_e32 v131, v133
	global_store_dwordx4 v[52:53], v[130:133], off
	v_and_b32_e32 v3, 0xffff0000, v108
	v_lshlrev_b32_e32 v2, 16, v108
	s_waitcnt vmcnt(2)
	v_pk_fma_f32 v[4:5], v[64:65], v[10:11], v[50:51] op_sel_hi:[1,1,0]
	v_pk_fma_f32 v[6:7], v[66:67], v[12:13], v[50:51] op_sel_hi:[1,1,0]
	v_pk_mul_f32 v[2:3], v[4:5], v[2:3]
	v_and_b32_e32 v5, 0xffff0000, v109
	v_lshlrev_b32_e32 v4, 16, v109
	v_pk_mul_f32 v[4:5], v[6:7], v[4:5]
	v_cvt_pk_bf16_f32 v130, v2, v3
	v_cvt_pk_bf16_f32 v131, v4, v5
	v_and_b32_e32 v3, 0xffff0000, v106
	v_lshlrev_b32_e32 v2, 16, v106
	s_waitcnt vmcnt(1)
	v_pk_fma_f32 v[4:5], v[122:123], v[14:15], v[50:51] op_sel_hi:[1,1,0]
	v_pk_fma_f32 v[6:7], v[124:125], v[16:17], v[50:51] op_sel_hi:[1,1,0]
	v_pk_mul_f32 v[2:3], v[4:5], v[2:3]
	v_and_b32_e32 v5, 0xffff0000, v107
	v_lshlrev_b32_e32 v4, 16, v107
	v_pk_mul_f32 v[4:5], v[6:7], v[4:5]
	v_cvt_pk_bf16_f32 v132, v2, v3
	v_cvt_pk_bf16_f32 v133, v4, v5
	s_nop 1
	v_permlane32_swap_b32_e32 v130, v132
	v_permlane32_swap_b32_e32 v131, v133
	global_store_dwordx4 v[52:53], v[130:133], off offset:32
	global_load_dwordx4 v[56:59], v[54:55], off offset:128
	global_load_dwordx4 v[60:63], v[54:55], off offset:160
	global_load_dwordx4 v[64:67], v[54:55], off offset:192
	global_load_dwordx4 v[106:109], v[54:55], off offset:224
	ds_read_b128 v[2:5], v121 offset:8704
	ds_read_b128 v[110:113], v121 offset:8736
	s_waitcnt lgkmcnt(1)
	v_mfma_f32_32x32x16_bf16 v[2:17], v[2:5], v[46:49], 0
	v_and_b32_e32 v69, 0xffff0000, v104
	v_lshlrev_b32_e32 v68, 16, v104
	s_waitcnt lgkmcnt(0)
	v_mfma_f32_32x32x16_bf16 v[2:17], v[110:113], v[42:45], v[2:17]
	ds_read_b128 v[110:113], v121 offset:8768
	s_waitcnt lgkmcnt(0)
	v_mfma_f32_32x32x16_bf16 v[2:17], v[110:113], v[38:41], v[2:17]
	ds_read_b128 v[110:113], v121 offset:8800
	s_waitcnt lgkmcnt(0)
	v_mfma_f32_32x32x16_bf16 v[2:17], v[110:113], v[34:37], v[2:17]
	ds_read_b128 v[110:113], v121 offset:8832
	s_waitcnt lgkmcnt(0)
	v_mfma_f32_32x32x16_bf16 v[2:17], v[110:113], v[30:33], v[2:17]
	ds_read_b128 v[110:113], v121 offset:8864
	s_waitcnt lgkmcnt(0)
	v_mfma_f32_32x32x16_bf16 v[2:17], v[110:113], v[26:29], v[2:17]
	ds_read_b128 v[110:113], v121 offset:8896
	s_waitcnt lgkmcnt(0)
	v_mfma_f32_32x32x16_bf16 v[2:17], v[110:113], v[22:25], v[2:17]
	ds_read_b128 v[110:113], v121 offset:8928
	s_waitcnt lgkmcnt(0)
	v_mfma_f32_32x32x16_bf16 v[2:17], v[110:113], v[18:21], v[2:17]
	s_waitcnt vmcnt(3)
	s_nop 10
	v_pk_fma_f32 v[2:3], v[56:57], v[2:3], v[50:51] op_sel_hi:[1,1,0]
	v_and_b32_e32 v57, 0xffff0000, v105
	v_lshlrev_b32_e32 v56, 16, v105
	v_pk_fma_f32 v[4:5], v[58:59], v[4:5], v[50:51] op_sel_hi:[1,1,0]
	v_pk_mul_f32 v[2:3], v[2:3], v[68:69]
	v_pk_mul_f32 v[4:5], v[4:5], v[56:57]
	v_cvt_pk_bf16_f32 v130, v2, v3
	v_cvt_pk_bf16_f32 v131, v4, v5
	v_and_b32_e32 v3, 0xffff0000, v102
	v_lshlrev_b32_e32 v2, 16, v102
	s_waitcnt vmcnt(2)
	v_pk_fma_f32 v[4:5], v[60:61], v[6:7], v[50:51] op_sel_hi:[1,1,0]
	v_pk_fma_f32 v[6:7], v[62:63], v[8:9], v[50:51] op_sel_hi:[1,1,0]
	v_pk_mul_f32 v[2:3], v[4:5], v[2:3]
	v_and_b32_e32 v5, 0xffff0000, v103
	v_lshlrev_b32_e32 v4, 16, v103
	v_pk_mul_f32 v[4:5], v[6:7], v[4:5]
	v_cvt_pk_bf16_f32 v132, v2, v3
	v_cvt_pk_bf16_f32 v133, v4, v5
	s_nop 1
	v_permlane32_swap_b32_e32 v130, v132
	v_permlane32_swap_b32_e32 v131, v133
	global_store_dwordx4 v[52:53], v[130:133], off offset:64
	v_and_b32_e32 v3, 0xffff0000, v100
	v_lshlrev_b32_e32 v2, 16, v100
	s_waitcnt vmcnt(2)
	v_pk_fma_f32 v[4:5], v[64:65], v[10:11], v[50:51] op_sel_hi:[1,1,0]
	v_pk_fma_f32 v[6:7], v[66:67], v[12:13], v[50:51] op_sel_hi:[1,1,0]
	v_pk_mul_f32 v[2:3], v[4:5], v[2:3]
	v_and_b32_e32 v5, 0xffff0000, v101
	v_lshlrev_b32_e32 v4, 16, v101
	v_pk_mul_f32 v[4:5], v[6:7], v[4:5]
	v_cvt_pk_bf16_f32 v130, v2, v3
	v_cvt_pk_bf16_f32 v131, v4, v5
	v_and_b32_e32 v3, 0xffff0000, v98
	v_lshlrev_b32_e32 v2, 16, v98
	s_waitcnt vmcnt(1)
	v_pk_fma_f32 v[4:5], v[106:107], v[14:15], v[50:51] op_sel_hi:[1,1,0]
	v_pk_fma_f32 v[6:7], v[108:109], v[16:17], v[50:51] op_sel_hi:[1,1,0]
	v_pk_mul_f32 v[2:3], v[4:5], v[2:3]
	v_and_b32_e32 v5, 0xffff0000, v99
	v_lshlrev_b32_e32 v4, 16, v99
	v_pk_mul_f32 v[4:5], v[6:7], v[4:5]
	v_cvt_pk_bf16_f32 v132, v2, v3
	v_cvt_pk_bf16_f32 v133, v4, v5
	s_nop 1
	v_permlane32_swap_b32_e32 v130, v132
	v_permlane32_swap_b32_e32 v131, v133
	global_store_dwordx4 v[52:53], v[130:133], off offset:96
	global_load_dwordx4 v[56:59], v[54:55], off offset:256
	global_load_dwordx4 v[60:63], v[54:55], off offset:288
	global_load_dwordx4 v[64:67], v[54:55], off offset:320
	global_load_dwordx4 v[98:101], v[54:55], off offset:352
	ds_read_b128 v[2:5], v121 offset:17408
	ds_read_b128 v[102:105], v121 offset:17440
	s_waitcnt lgkmcnt(1)
	v_mfma_f32_32x32x16_bf16 v[2:17], v[2:5], v[46:49], 0
	v_and_b32_e32 v69, 0xffff0000, v96
	v_lshlrev_b32_e32 v68, 16, v96
	s_waitcnt lgkmcnt(0)
	v_mfma_f32_32x32x16_bf16 v[2:17], v[102:105], v[42:45], v[2:17]
	ds_read_b128 v[102:105], v121 offset:17472
	s_waitcnt lgkmcnt(0)
	v_mfma_f32_32x32x16_bf16 v[2:17], v[102:105], v[38:41], v[2:17]
	ds_read_b128 v[102:105], v121 offset:17504
	s_waitcnt lgkmcnt(0)
	v_mfma_f32_32x32x16_bf16 v[2:17], v[102:105], v[34:37], v[2:17]
	ds_read_b128 v[102:105], v121 offset:17536
	s_waitcnt lgkmcnt(0)
	v_mfma_f32_32x32x16_bf16 v[2:17], v[102:105], v[30:33], v[2:17]
	ds_read_b128 v[102:105], v121 offset:17568
	s_waitcnt lgkmcnt(0)
	v_mfma_f32_32x32x16_bf16 v[2:17], v[102:105], v[26:29], v[2:17]
	ds_read_b128 v[102:105], v121 offset:17600
	s_waitcnt lgkmcnt(0)
	v_mfma_f32_32x32x16_bf16 v[2:17], v[102:105], v[22:25], v[2:17]
	ds_read_b128 v[102:105], v121 offset:17632
	s_waitcnt lgkmcnt(0)
	v_mfma_f32_32x32x16_bf16 v[2:17], v[102:105], v[18:21], v[2:17]
	s_waitcnt vmcnt(3)
	s_nop 10
	v_pk_fma_f32 v[2:3], v[56:57], v[2:3], v[50:51] op_sel_hi:[1,1,0]
	v_and_b32_e32 v57, 0xffff0000, v97
	v_lshlrev_b32_e32 v56, 16, v97
	v_pk_fma_f32 v[4:5], v[58:59], v[4:5], v[50:51] op_sel_hi:[1,1,0]
	v_pk_mul_f32 v[2:3], v[2:3], v[68:69]
	v_pk_mul_f32 v[4:5], v[4:5], v[56:57]
	v_cvt_pk_bf16_f32 v130, v2, v3
	v_cvt_pk_bf16_f32 v131, v4, v5
	v_and_b32_e32 v3, 0xffff0000, v94
	v_lshlrev_b32_e32 v2, 16, v94
	s_waitcnt vmcnt(2)
	v_pk_fma_f32 v[4:5], v[60:61], v[6:7], v[50:51] op_sel_hi:[1,1,0]
	v_pk_fma_f32 v[6:7], v[62:63], v[8:9], v[50:51] op_sel_hi:[1,1,0]
	v_pk_mul_f32 v[2:3], v[4:5], v[2:3]
	v_and_b32_e32 v5, 0xffff0000, v95
	v_lshlrev_b32_e32 v4, 16, v95
	v_pk_mul_f32 v[4:5], v[6:7], v[4:5]
	v_cvt_pk_bf16_f32 v132, v2, v3
	v_cvt_pk_bf16_f32 v133, v4, v5
	s_nop 1
	v_permlane32_swap_b32_e32 v130, v132
	v_permlane32_swap_b32_e32 v131, v133
	global_store_dwordx4 v[52:53], v[130:133], off offset:128
	v_and_b32_e32 v3, 0xffff0000, v92
	v_lshlrev_b32_e32 v2, 16, v92
	s_waitcnt vmcnt(2)
	v_pk_fma_f32 v[4:5], v[64:65], v[10:11], v[50:51] op_sel_hi:[1,1,0]
	v_pk_fma_f32 v[6:7], v[66:67], v[12:13], v[50:51] op_sel_hi:[1,1,0]
	v_pk_mul_f32 v[2:3], v[4:5], v[2:3]
	v_and_b32_e32 v5, 0xffff0000, v93
	v_lshlrev_b32_e32 v4, 16, v93
	v_pk_mul_f32 v[4:5], v[6:7], v[4:5]
	v_cvt_pk_bf16_f32 v130, v2, v3
	v_cvt_pk_bf16_f32 v131, v4, v5
	v_and_b32_e32 v3, 0xffff0000, v90
	v_lshlrev_b32_e32 v2, 16, v90
	s_waitcnt vmcnt(1)
	v_pk_fma_f32 v[4:5], v[98:99], v[14:15], v[50:51] op_sel_hi:[1,1,0]
	v_pk_fma_f32 v[6:7], v[100:101], v[16:17], v[50:51] op_sel_hi:[1,1,0]
	v_pk_mul_f32 v[2:3], v[4:5], v[2:3]
	v_and_b32_e32 v5, 0xffff0000, v91
	v_lshlrev_b32_e32 v4, 16, v91
	v_pk_mul_f32 v[4:5], v[6:7], v[4:5]
	v_cvt_pk_bf16_f32 v132, v2, v3
	v_cvt_pk_bf16_f32 v133, v4, v5
	s_nop 1
	v_permlane32_swap_b32_e32 v130, v132
	v_permlane32_swap_b32_e32 v131, v133
	global_store_dwordx4 v[52:53], v[130:133], off offset:160
	global_load_dwordx4 v[56:59], v[54:55], off offset:384
	global_load_dwordx4 v[60:63], v[54:55], off offset:416
	global_load_dwordx4 v[64:67], v[54:55], off offset:448
	global_load_dwordx4 v[90:93], v[54:55], off offset:480
	ds_read_b128 v[2:5], v121 offset:26112
	ds_read_b128 v[94:97], v121 offset:26144
	s_waitcnt lgkmcnt(1)
	v_mfma_f32_32x32x16_bf16 v[2:17], v[2:5], v[46:49], 0
	s_waitcnt lgkmcnt(0)
	v_mfma_f32_32x32x16_bf16 v[2:17], v[94:97], v[42:45], v[2:17]
	ds_read_b128 v[42:45], v121 offset:26176
	s_waitcnt lgkmcnt(0)
	v_mfma_f32_32x32x16_bf16 v[2:17], v[42:45], v[38:41], v[2:17]
	ds_read_b128 v[38:41], v121 offset:26208
	s_waitcnt lgkmcnt(0)
	v_mfma_f32_32x32x16_bf16 v[2:17], v[38:41], v[34:37], v[2:17]
	ds_read_b128 v[34:37], v121 offset:26240
	s_waitcnt lgkmcnt(0)
	v_mfma_f32_32x32x16_bf16 v[2:17], v[34:37], v[30:33], v[2:17]
	ds_read_b128 v[30:33], v121 offset:26272
	s_waitcnt lgkmcnt(0)
	v_mfma_f32_32x32x16_bf16 v[2:17], v[30:33], v[26:29], v[2:17]
	ds_read_b128 v[26:29], v121 offset:26304
	s_waitcnt lgkmcnt(0)
	v_mfma_f32_32x32x16_bf16 v[2:17], v[26:29], v[22:25], v[2:17]
	ds_read_b128 v[22:25], v121 offset:26336
	s_waitcnt lgkmcnt(0)
	v_mfma_f32_32x32x16_bf16 v[2:17], v[22:25], v[18:21], v[2:17]
	v_and_b32_e32 v19, 0xffff0000, v88
	v_lshlrev_b32_e32 v18, 16, v88
	s_waitcnt vmcnt(3)
	s_nop 8
	v_pk_fma_f32 v[2:3], v[56:57], v[2:3], v[50:51] op_sel_hi:[1,1,0]
	v_pk_fma_f32 v[4:5], v[58:59], v[4:5], v[50:51] op_sel_hi:[1,1,0]
	v_pk_mul_f32 v[2:3], v[2:3], v[18:19]
	v_and_b32_e32 v19, 0xffff0000, v89
	v_lshlrev_b32_e32 v18, 16, v89
	v_pk_mul_f32 v[4:5], v[4:5], v[18:19]
	v_cvt_pk_bf16_f32 v130, v2, v3
	v_cvt_pk_bf16_f32 v131, v4, v5
	v_and_b32_e32 v3, 0xffff0000, v86
	v_lshlrev_b32_e32 v2, 16, v86
	s_waitcnt vmcnt(2)
	v_pk_fma_f32 v[4:5], v[60:61], v[6:7], v[50:51] op_sel_hi:[1,1,0]
	v_pk_fma_f32 v[6:7], v[62:63], v[8:9], v[50:51] op_sel_hi:[1,1,0]
	v_pk_mul_f32 v[2:3], v[4:5], v[2:3]
	v_and_b32_e32 v5, 0xffff0000, v87
	v_lshlrev_b32_e32 v4, 16, v87
	v_pk_mul_f32 v[4:5], v[6:7], v[4:5]
	v_cvt_pk_bf16_f32 v132, v2, v3
	v_cvt_pk_bf16_f32 v133, v4, v5
	s_nop 1
	v_permlane32_swap_b32_e32 v130, v132
	v_permlane32_swap_b32_e32 v131, v133
	global_store_dwordx4 v[52:53], v[130:133], off offset:192
	v_and_b32_e32 v3, 0xffff0000, v84
	v_lshlrev_b32_e32 v2, 16, v84
	s_waitcnt vmcnt(2)
	v_pk_fma_f32 v[4:5], v[64:65], v[10:11], v[50:51] op_sel_hi:[1,1,0]
	v_pk_fma_f32 v[6:7], v[66:67], v[12:13], v[50:51] op_sel_hi:[1,1,0]
	v_pk_mul_f32 v[2:3], v[4:5], v[2:3]
	v_and_b32_e32 v5, 0xffff0000, v85
	v_lshlrev_b32_e32 v4, 16, v85
	v_pk_mul_f32 v[4:5], v[6:7], v[4:5]
	v_cvt_pk_bf16_f32 v130, v2, v3
	v_cvt_pk_bf16_f32 v131, v4, v5
	v_and_b32_e32 v3, 0xffff0000, v82
	v_lshlrev_b32_e32 v2, 16, v82
	s_waitcnt vmcnt(1)
	v_pk_fma_f32 v[4:5], v[90:91], v[14:15], v[50:51] op_sel_hi:[1,1,0]
	v_pk_fma_f32 v[6:7], v[92:93], v[16:17], v[50:51] op_sel_hi:[1,1,0]
	v_pk_mul_f32 v[2:3], v[4:5], v[2:3]
	v_and_b32_e32 v5, 0xffff0000, v83
	v_lshlrev_b32_e32 v4, 16, v83
	v_pk_mul_f32 v[4:5], v[6:7], v[4:5]
	v_cvt_pk_bf16_f32 v132, v2, v3
	v_cvt_pk_bf16_f32 v133, v4, v5
	s_nop 1
	v_permlane32_swap_b32_e32 v130, v132
	v_permlane32_swap_b32_e32 v131, v133
	global_store_dwordx4 v[52:53], v[130:133], off offset:224
	s_cbranch_scc0 .LBB0_675

.LBB0_680:
	v_mov_b32_e32 v0, v97
	s_nop 1
	v_permlane32_swap_b32_e32 v97, v0
	v_add_f32_e32 v0, v97, v0
	v_div_scale_f32 v34, s[0:1], v0, v0, 1.0
	v_rcp_f32_e32 v35, v34
	v_mov_b32_e32 v101, v1
	v_readlane_b32 s72, v254, 53
	v_readlane_b32 s80, v254, 51
	v_fma_f32 v36, -v34, v35, 1.0
	v_fmac_f32_e32 v35, v36, v35
	v_div_scale_f32 v36, vcc, 1.0, v0, 1.0
	v_mul_f32_e32 v37, v36, v35
	v_fma_f32 v38, -v34, v37, v36
	v_fmac_f32_e32 v37, v38, v35
	v_fma_f32 v34, -v34, v37, v36
	v_div_fmas_f32 v34, v34, v35, v37
	v_div_fixup_f32 v34, v34, v0, 1.0
	v_lshl_add_u64 v[36:37], s[24:25], 0, v[100:101]
	v_lshlrev_b32_e32 v0, 1, v94
	v_lshl_add_u64 v[36:37], v[36:37], 0, v[0:1]
	v_lshl_add_u64 v[36:37], v[36:37], 0, v[0:1]
	v_pk_mul_f32 v[18:19], v[18:19], v[34:35] op_sel_hi:[1,0]
	v_pk_mul_f32 v[20:21], v[20:21], v[34:35] op_sel_hi:[1,0]
	v_pk_mul_f32 v[22:23], v[22:23], v[34:35] op_sel_hi:[1,0]
	v_pk_mul_f32 v[24:25], v[24:25], v[34:35] op_sel_hi:[1,0]
	v_cvt_pk_bf16_f32 v172, v18, v19
	v_cvt_pk_bf16_f32 v173, v20, v21
	v_cvt_pk_bf16_f32 v174, v22, v23
	v_cvt_pk_bf16_f32 v175, v24, v25
	s_nop 1
	v_permlane32_swap_b32_e32 v172, v174
	v_permlane32_swap_b32_e32 v173, v175
	global_store_dwordx4 v[36:37], v[172:175], off
	v_pk_mul_f32 v[26:27], v[26:27], v[34:35] op_sel_hi:[1,0]
	v_pk_mul_f32 v[28:29], v[28:29], v[34:35] op_sel_hi:[1,0]
	v_pk_mul_f32 v[30:31], v[30:31], v[34:35] op_sel_hi:[1,0]
	v_pk_mul_f32 v[32:33], v[32:33], v[34:35] op_sel_hi:[1,0]
	v_cvt_pk_bf16_f32 v176, v26, v27
	v_cvt_pk_bf16_f32 v177, v28, v29
	v_cvt_pk_bf16_f32 v178, v30, v31
	v_cvt_pk_bf16_f32 v179, v32, v33
	s_nop 1
	v_permlane32_swap_b32_e32 v176, v178
	v_permlane32_swap_b32_e32 v177, v179
	global_store_dwordx4 v[36:37], v[176:179], off offset:32
	v_pk_mul_f32 v[2:3], v[2:3], v[34:35] op_sel_hi:[1,0]
	v_pk_mul_f32 v[4:5], v[4:5], v[34:35] op_sel_hi:[1,0]
	v_pk_mul_f32 v[6:7], v[6:7], v[34:35] op_sel_hi:[1,0]
	v_pk_mul_f32 v[8:9], v[8:9], v[34:35] op_sel_hi:[1,0]
	v_cvt_pk_bf16_f32 v180, v2, v3
	v_cvt_pk_bf16_f32 v181, v4, v5
	v_cvt_pk_bf16_f32 v182, v6, v7
	v_cvt_pk_bf16_f32 v183, v8, v9
	s_nop 1
	v_permlane32_swap_b32_e32 v180, v182
	v_permlane32_swap_b32_e32 v181, v183
	global_store_dwordx4 v[36:37], v[180:183], off offset:64
	v_pk_mul_f32 v[10:11], v[10:11], v[34:35] op_sel_hi:[1,0]
	v_pk_mul_f32 v[12:13], v[12:13], v[34:35] op_sel_hi:[1,0]
	v_pk_mul_f32 v[14:15], v[14:15], v[34:35] op_sel_hi:[1,0]
	v_pk_mul_f32 v[16:17], v[16:17], v[34:35] op_sel_hi:[1,0]
	v_cvt_pk_bf16_f32 v184, v10, v11
	v_cvt_pk_bf16_f32 v185, v12, v13
	v_cvt_pk_bf16_f32 v186, v14, v15
	v_cvt_pk_bf16_f32 v187, v16, v17
	s_nop 1
	v_permlane32_swap_b32_e32 v184, v186
	v_permlane32_swap_b32_e32 v185, v187
	global_store_dwordx4 v[36:37], v[184:187], off offset:96
	v_readlane_b32 s82, v254, 49
	v_readlane_b32 s86, v254, 62
	s_mov_b32 s93, 0x1b000
	s_mov_b32 s70, 0x9000
	s_mov_b32 s71, 0x12000
	s_mov_b32 s68, 0x800000
	s_movk_i32 s69, 0xfe00
	s_mov_b32 s92, 0x48000
	s_mov_b32 s33, 0x24000
	s_mov_b32 s34, 0x2d000
	s_mov_b32 s35, 0x36000
	s_mov_b32 s20, 0x3f000
	s_mov_b32 s16, 0x63000
	s_mov_b32 s88, 0x7e000
	s_mov_b32 s89, 0xc6000
	s_mov_b32 s90, 0xe1000
	v_readlane_b32 s73, v254, 54
	v_readlane_b32 s81, v254, 52
	v_readlane_b32 s83, v254, 50
	v_readlane_b32 s84, v254, 60
	v_readlane_b32 s85, v254, 61
	v_readlane_b32 s87, v254, 63
	s_mov_b64 s[0:1], 0
